# attention phase: static s_setprio 1 for waves 4-7 (younger half)
# speedup vs baseline: 1.0108x; 1.0106x over previous
.Lq_pf0:
	s_cmp_lt_u32 s33, 4
	s_cbranch_scc1 .Lprio_skip
	s_setprio 1

.LBB0_777:
	s_setprio 0
	s_mov_b32 s3, s33
	v_mbcnt_lo_u32_b32 v0, -1, 0
	v_mbcnt_hi_u32_b32 v0, -1, v0
	s_waitcnt vmcnt(0)
	s_nop 0
	v_lshl_or_b32 v0, s3, 6, v0
	v_cmp_eq_u32_e32 vcc, 0, v0
	s_barrier
	s_and_saveexec_b64 s[4:5], vcc
	s_cbranch_execz .LBB0_829
	v_readlane_b32 s6, v254, 51
	s_getreg_b32 s3, hwreg(HW_REG_XCC_ID, 0, 4)
	s_waitcnt vmcnt(0) expcnt(0) lgkmcnt(0)
	v_mov_b32_e32 v0, s6
	ds_read_b32 v2, v0
	v_readlane_b32 s6, v254, 52
	s_and_b32 s3, s3, 15
	s_waitcnt lgkmcnt(0)
	v_cmp_ne_u32_e32 vcc, 0, v2
	v_mov_b32_e32 v0, s6
	ds_read_b32 v0, v0
	s_cbranch_vccnz .LBB0_793
	s_mov_b32 s12, 1
	s_branch .LBB0_781
